# layer-0 norm phase: row sum-of-squares butterfly via DPP + permlane swaps instead of 12 ds_bpermute round trips per 4-row group (same add order)
# speedup vs baseline: 1.0032x; 1.0032x over previous
.LBB0_492:
	s_add_i32 s4, s2, -3
	s_add_i32 s0, s2, 0xffff7ffd
	s_ashr_i32 s5, s4, 31
	s_cmpk_lt_i32 s14, 0x2000
	s_mov_b32 s8, 0x358637bd
	s_cselect_b32 s1, s5, 0
	s_cselect_b32 s0, s4, s0
	v_mov_b64_e32 v[92:93], s[8:9]
	s_cselect_b32 s3, s65, s69
	s_cselect_b32 s8, s64, s68
	s_lshl_b64 s[0:1], s[0:1], 12
	s_add_u32 s0, s8, s0
	s_addc_u32 s1, s3, s1
	s_add_i32 s8, s2, -2
	global_load_dwordx4 v[36:39], v[90:91], off
	global_load_dwordx4 v[40:43], v[90:91], off offset:1024
	global_load_dwordx4 v[76:79], v[90:91], off offset:2048
	global_load_dwordx4 v[80:83], v[90:91], off offset:3072
	s_add_i32 s3, s2, 0xffff7ffe
	global_load_dwordx4 v[56:59], v120, s[0:1]
	global_load_dwordx4 v[48:51], v120, s[0:1] offset:1024
	global_load_dwordx4 v[44:47], v120, s[0:1] offset:3072
	global_load_dwordx4 v[52:55], v120, s[0:1] offset:2048
	s_ashr_i32 s9, s8, 31
	s_cmp_lt_i32 s8, 0x8000
	s_cselect_b32 s1, s9, 0
	s_cselect_b32 s0, s8, s3
	s_cselect_b32 s3, s65, s69
	s_cselect_b32 s10, s64, s68
	s_lshl_b64 s[0:1], s[0:1], 12
	s_add_u32 s0, s10, s0
	s_addc_u32 s1, s3, s1
	s_add_i32 s10, s2, -1
	s_add_i32 s3, s2, 0xffff7fff
	global_load_dwordx4 v[72:75], v120, s[0:1]
	global_load_dwordx4 v[64:67], v120, s[0:1] offset:1024
	global_load_dwordx4 v[60:63], v120, s[0:1] offset:3072
	global_load_dwordx4 v[68:71], v120, s[0:1] offset:2048
	s_ashr_i32 s11, s10, 31
	s_cmp_lt_i32 s10, 0x8000
	s_cselect_b32 s1, s11, 0
	s_cselect_b32 s0, s10, s3
	s_cselect_b32 s3, s65, s69
	s_cselect_b32 s12, s64, s68
	s_lshl_b64 s[0:1], s[0:1], 12
	s_add_u32 s0, s12, s0
	s_addc_u32 s1, s3, s1
	global_load_dwordx4 v[12:15], v120, s[0:1]
	global_load_dwordx4 v[8:11], v120, s[0:1] offset:1024
	global_load_dwordx4 v[4:7], v120, s[0:1] offset:2048
	global_load_dwordx4 v[0:3], v120, s[0:1] offset:3072
	s_ashr_i32 s3, s2, 31
	s_add_i32 s12, s2, 0xffff8000
	s_cmp_lt_i32 s2, 0x8000
	s_cselect_b32 s1, s3, 0
	s_cselect_b32 s0, s2, s12
	s_cselect_b32 s12, s65, s69
	s_cselect_b32 s13, s64, s68
	s_lshl_b64 s[0:1], s[0:1], 12
	s_add_u32 s0, s13, s0
	s_addc_u32 s1, s12, s1
	s_min_i32 s12, s14, 0x2000
	global_load_dwordx4 v[28:31], v120, s[0:1]
	global_load_dwordx4 v[24:27], v120, s[0:1] offset:1024
	global_load_dwordx4 v[20:23], v120, s[0:1] offset:2048
	global_load_dwordx4 v[16:19], v120, s[0:1] offset:3072
	s_ashr_i32 s0, s12, 9
	s_mul_hi_i32 s1, s0, 0x6000
	s_mulk_i32 s0, 0x6000
	s_add_u32 s12, s34, s0
	s_addc_u32 s13, s35, s1
	s_add_u32 s0, s12, 0x1000
	s_addc_u32 s1, s13, 0
	global_load_dwordx4 v[32:35], v121, s[0:1]
	global_load_dwordx4 v[104:107], v122, s[0:1]
	global_load_dwordx4 v[126:129], v123, s[0:1]
	s_lshl_b64 s[8:9], s[8:9], 11
	s_add_i32 s14, s14, s29
	s_waitcnt vmcnt(0)
	v_pk_mul_f32 v[84:85], v[58:59], v[58:59]
	v_pk_mul_f32 v[86:87], v[56:57], v[56:57]
	v_pk_mul_f32 v[94:95], v[50:51], v[50:51]
	v_pk_mul_f32 v[96:97], v[48:49], v[48:49]
	v_pk_mov_b32 v[98:99], v[86:87], v[84:85] op_sel:[1,0]
	v_mov_b32_e32 v87, v85
	v_pk_mov_b32 v[84:85], v[96:97], v[94:95] op_sel:[1,0]
	v_mov_b32_e32 v97, v95
	v_mul_f32_e32 v94, v53, v53
	v_pk_add_f32 v[86:87], v[98:99], v[86:87]
	v_mul_f32_e32 v98, v55, v55
	v_pk_add_f32 v[84:85], v[84:85], v[96:97]
	v_mul_f32_e32 v100, v44, v44
	v_mul_f32_e32 v101, v45, v45
	v_mul_f32_e32 v102, v46, v46
	v_mul_f32_e32 v103, v47, v47
	v_pk_fma_f32 v[94:95], v[52:53], v[52:53], v[94:95] op_sel_hi:[1,1,0]
	v_pk_fma_f32 v[98:99], v[54:55], v[54:55], v[98:99] op_sel_hi:[1,1,0]
	v_pk_add_f32 v[86:87], v[86:87], v[86:87] op_sel:[0,1] op_sel_hi:[1,0]
	v_pk_add_f32 v[84:85], v[84:85], v[84:85] op_sel:[0,1] op_sel_hi:[1,0]
	v_mov_b32_e32 v95, v102
	v_mov_b32_e32 v99, v103
	v_mov_b32_e32 v87, v100
	v_mov_b32_e32 v85, v101
	v_pk_add_f32 v[94:95], v[94:95], v[98:99]
	v_pk_add_f32 v[84:85], v[86:87], v[84:85]
	v_pk_mul_f32 v[86:87], v[72:73], v[72:73]
	v_pk_add_f32 v[94:95], v[84:85], v[94:95]
	v_pk_mul_f32 v[84:85], v[74:75], v[74:75]
	v_pk_mul_f32 v[96:97], v[66:67], v[66:67]
	v_pk_mul_f32 v[98:99], v[64:65], v[64:65]
	v_pk_mov_b32 v[100:101], v[86:87], v[84:85] op_sel:[1,0]
	v_mov_b32_e32 v87, v85
	v_pk_mov_b32 v[84:85], v[98:99], v[96:97] op_sel:[1,0]
	v_mov_b32_e32 v99, v97
	v_pk_add_f32 v[86:87], v[100:101], v[86:87]
	v_mul_f32_e32 v96, v69, v69
	v_pk_add_f32 v[84:85], v[84:85], v[98:99]
	v_mul_f32_e32 v98, v71, v71
	v_mul_f32_e32 v102, v60, v60
	v_mul_f32_e32 v103, v61, v61
	v_mul_f32_e32 v108, v62, v62
	v_mul_f32_e32 v109, v63, v63
	v_pk_fma_f32 v[96:97], v[68:69], v[68:69], v[96:97] op_sel_hi:[1,1,0]
	v_pk_fma_f32 v[98:99], v[70:71], v[70:71], v[98:99] op_sel_hi:[1,1,0]
	v_pk_add_f32 v[86:87], v[86:87], v[86:87] op_sel:[0,1] op_sel_hi:[1,0]
	v_pk_add_f32 v[84:85], v[84:85], v[84:85] op_sel:[0,1] op_sel_hi:[1,0]
	v_mov_b32_e32 v97, v108
	v_mov_b32_e32 v99, v109
	v_mov_b32_e32 v87, v102
	v_mov_b32_e32 v85, v103
	v_pk_add_f32 v[96:97], v[96:97], v[98:99]
	v_pk_add_f32 v[84:85], v[86:87], v[84:85]
	v_pk_mul_f32 v[86:87], v[14:15], v[14:15]
	v_pk_add_f32 v[84:85], v[84:85], v[96:97]
	v_pk_mul_f32 v[96:97], v[12:13], v[12:13]
	v_pk_mul_f32 v[98:99], v[10:11], v[10:11]
	v_pk_mul_f32 v[100:101], v[8:9], v[8:9]
	v_pk_mov_b32 v[102:103], v[96:97], v[86:87] op_sel:[1,0]
	v_mov_b32_e32 v97, v87
	v_pk_mov_b32 v[108:109], v[100:101], v[98:99] op_sel:[1,0]
	v_mov_b32_e32 v101, v99
	v_mov_b32_e32 v99, v94
	v_mov_b32_e32 v98, v84
	v_mov_b32_e32 v94, v85
	global_load_dwordx4 v[84:87], v124, s[0:1]
	v_pk_add_f32 v[96:97], v[102:103], v[96:97]
	v_mul_f32_e32 v103, v2, v2
	v_mul_f32_e32 v102, v5, v5
	v_pk_add_f32 v[100:101], v[108:109], v[100:101]
	v_pk_fma_f32 v[108:109], v[4:5], v[4:5], v[102:103] op_sel_hi:[1,1,0]
	v_mul_f32_e32 v110, v3, v3
	v_mov_b32_e32 v109, v103
	v_pk_add_f32 v[102:103], v[98:99], v[94:95]
	v_mul_f32_e32 v94, v7, v7
	v_pk_fma_f32 v[94:95], v[6:7], v[6:7], v[94:95] op_sel_hi:[1,1,0]
	v_mul_f32_e32 v98, v0, v0
	v_mov_b32_e32 v95, v110
	v_pk_add_f32 v[108:109], v[108:109], v[94:95]
	v_mul_f32_e32 v99, v1, v1
	v_pk_add_f32 v[94:95], v[96:97], v[96:97] op_sel:[0,1] op_sel_hi:[1,0]
	v_pk_add_f32 v[96:97], v[100:101], v[100:101] op_sel:[0,1] op_sel_hi:[1,0]
	v_mov_b32_e32 v95, v98
	v_mov_b32_e32 v97, v99
	v_pk_add_f32 v[98:99], v[106:107], 1.0 op_sel_hi:[1,0]
	v_pk_add_f32 v[100:101], v[104:105], 1.0 op_sel_hi:[1,0]
	v_pk_add_f32 v[104:105], v[128:129], 1.0 op_sel_hi:[1,0]
	v_pk_add_f32 v[106:107], v[126:127], 1.0 op_sel_hi:[1,0]
	v_pk_add_f32 v[110:111], v[94:95], v[96:97]
	v_pk_mul_f32 v[78:79], v[78:79], v[104:105]
	v_pk_mul_f32 v[76:77], v[76:77], v[106:107]
	v_pk_mul_f32 v[112:113], v[30:31], v[30:31]
	v_pk_mul_f32 v[104:105], v[28:29], v[28:29]
	v_pk_mul_f32 v[106:107], v[24:25], v[24:25]
	v_pk_add_f32 v[108:109], v[110:111], v[108:109]
	v_pk_mov_b32 v[110:111], v[104:105], v[112:113] op_sel:[1,0]
	v_mov_b32_e32 v105, v113
	v_pk_add_f32 v[94:95], v[34:35], 1.0 op_sel_hi:[1,0]
	v_pk_add_f32 v[96:97], v[32:33], 1.0 op_sel_hi:[1,0]
	global_load_dwordx4 v[32:35], v121, s[12:13]
	v_pk_mul_f32 v[94:95], v[38:39], v[94:95]
	v_pk_mul_f32 v[96:97], v[36:37], v[96:97]
	global_load_dwordx4 v[36:39], v121, s[12:13] offset:1024
	v_pk_mul_f32 v[98:99], v[42:43], v[98:99]
	v_pk_mul_f32 v[100:101], v[40:41], v[100:101]
	global_load_dwordx4 v[40:43], v121, s[12:13] offset:2048
	v_mul_f32_e32 v125, v18, v18
	v_mul_f32_e32 v126, v19, v19
	s_waitcnt vmcnt(0)
	v_pk_add_f32 v[84:85], v[84:85], 1.0 op_sel_hi:[1,0]
	s_nop 0
	v_pk_mul_f32 v[80:81], v[80:81], v[84:85]
	v_pk_mul_f32 v[84:85], v[26:27], v[26:27]
	v_pk_add_f32 v[86:87], v[86:87], 1.0 op_sel_hi:[1,0]
	v_pk_mov_b32 v[112:113], v[106:107], v[84:85] op_sel:[1,0]
	v_mov_b32_e32 v107, v85
	v_pk_mul_f32 v[82:83], v[82:83], v[86:87]
	v_pk_add_f32 v[106:107], v[112:113], v[106:107]
	v_mul_f32_e32 v112, v16, v16
	v_pk_add_f32 v[106:107], v[106:107], v[106:107] op_sel:[0,1] op_sel_hi:[1,0]
	s_nop 1
	v_add_f32_dpp v84, v102, v102 quad_perm:[1,0,3,2] row_mask:0xf bank_mask:0xf
	v_add_f32_dpp v85, v103, v103 quad_perm:[1,0,3,2] row_mask:0xf bank_mask:0xf
	s_nop 1
	v_add_f32_dpp v84, v84, v84 quad_perm:[2,3,0,1] row_mask:0xf bank_mask:0xf
	v_add_f32_dpp v85, v85, v85 quad_perm:[2,3,0,1] row_mask:0xf bank_mask:0xf
	s_nop 1
	v_add_f32_dpp v84, v84, v84 row_half_mirror row_mask:0xf bank_mask:0xf
	v_add_f32_dpp v85, v85, v85 row_half_mirror row_mask:0xf bank_mask:0xf
	s_nop 1
	v_add_f32_dpp v84, v84, v84 row_mirror row_mask:0xf bank_mask:0xf
	v_add_f32_dpp v85, v85, v85 row_mirror row_mask:0xf bank_mask:0xf
	v_mov_b32_e32 v86, v84
	v_mov_b32_e32 v87, v85
	s_nop 1
	v_permlane16_swap_b32_e32 v84, v86
	v_permlane16_swap_b32_e32 v85, v87
	v_pk_add_f32 v[84:85], v[84:85], v[86:87]
	v_mov_b32_e32 v86, v84
	v_mov_b32_e32 v87, v85
	s_nop 1
	v_permlane32_swap_b32_e32 v84, v86
	v_permlane32_swap_b32_e32 v85, v87
	v_pk_add_f32 v[84:85], v[84:85], v[86:87]
	s_nop 0
	v_pk_fma_f32 v[84:85], v[84:85], s[20:21], v[92:93] op_sel_hi:[1,0,0]
	s_nop 0
	v_mul_f32_e32 v86, 0x4b800000, v85
	v_cmp_gt_f32_e64 s[0:1], s18, v85
	v_mul_f32_e32 v87, 0x4b800000, v84
	v_cmp_gt_f32_e32 vcc, s18, v84
	v_cndmask_b32_e64 v85, v85, v86, s[0:1]
	v_rsq_f32_e32 v85, v85
	v_cndmask_b32_e32 v84, v84, v87, vcc
	v_rsq_f32_e32 v102, v84
	v_mul_f32_e32 v84, 0x45800000, v85
	v_cndmask_b32_e64 v86, v85, v84, s[0:1]
	v_pk_mul_f32 v[84:85], v[50:51], v[86:87] op_sel_hi:[1,0]
	v_pk_mul_f32 v[50:51], v[52:53], v[86:87] op_sel_hi:[1,0]
	v_pk_mul_f32 v[52:53], v[44:45], v[86:87] op_sel_hi:[1,0]
	v_mul_f32_e32 v44, 0x45800000, v102
	v_cndmask_b32_e32 v44, v102, v44, vcc
	v_pk_mul_f32 v[56:57], v[56:57], v[86:87] op_sel_hi:[1,0]
	v_pk_mul_f32 v[58:59], v[58:59], v[86:87] op_sel_hi:[1,0]
	v_pk_mul_f32 v[48:49], v[48:49], v[86:87] op_sel_hi:[1,0]
	v_pk_mul_f32 v[54:55], v[54:55], v[86:87] op_sel_hi:[1,0]
	v_pk_mul_f32 v[86:87], v[46:47], v[86:87] op_sel_hi:[1,0]
	v_pk_mul_f32 v[72:73], v[72:73], v[44:45] op_sel_hi:[1,0]
	v_pk_mul_f32 v[74:75], v[74:75], v[44:45] op_sel_hi:[1,0]
	v_pk_mul_f32 v[64:65], v[64:65], v[44:45] op_sel_hi:[1,0]
	v_pk_mul_f32 v[102:103], v[66:67], v[44:45] op_sel_hi:[1,0]
	v_pk_mul_f32 v[66:67], v[68:69], v[44:45] op_sel_hi:[1,0]
	v_pk_mul_f32 v[68:69], v[70:71], v[44:45] op_sel_hi:[1,0]
	v_pk_mul_f32 v[60:61], v[60:61], v[44:45] op_sel_hi:[1,0]
	v_pk_mul_f32 v[62:63], v[62:63], v[44:45] op_sel_hi:[1,0]
	global_load_dwordx4 v[44:47], v121, s[12:13] offset:3072
	v_pk_add_f32 v[70:71], v[110:111], v[104:105]
	v_mul_f32_e32 v104, v21, v21
	v_mul_f32_e32 v110, v23, v23
	v_pk_add_f32 v[70:71], v[70:71], v[70:71] op_sel:[0,1] op_sel_hi:[1,0]
	v_pk_fma_f32 v[104:105], v[20:21], v[20:21], v[104:105] op_sel_hi:[1,1,0]
	v_pk_fma_f32 v[110:111], v[22:23], v[22:23], v[110:111] op_sel_hi:[1,1,0]
	v_mov_b32_e32 v71, v112
	v_mul_f32_e32 v112, v17, v17
	v_mov_b32_e32 v105, v125
	v_mov_b32_e32 v111, v126
	v_mov_b32_e32 v107, v112
	v_pk_add_f32 v[110:111], v[104:105], v[110:111]
	v_pk_add_f32 v[70:71], v[70:71], v[106:107]
	s_lshl_b64 s[12:13], s[4:5], 11
	v_pk_add_f32 v[70:71], v[70:71], v[110:111]
	v_mov_b32_e32 v111, v108
	v_mov_b32_e32 v110, v70
	v_mov_b32_e32 v108, v71
	v_pk_add_f32 v[108:109], v[110:111], v[108:109]
	s_lshl_b64 s[0:1], s[2:3], 11
	v_pk_fma_f32 v[58:59], v[94:95], v[58:59], v[34:35]
	v_pk_fma_f32 v[56:57], v[96:97], v[56:57], v[32:33]
	v_lshl_add_u64 v[104:105], v[88:89], 0, s[12:13]
	s_nop 1
	v_add_f32_dpp v108, v108, v108 quad_perm:[1,0,3,2] row_mask:0xf bank_mask:0xf
	v_add_f32_dpp v109, v109, v109 quad_perm:[1,0,3,2] row_mask:0xf bank_mask:0xf
	v_pk_fma_f32 v[48:49], v[100:101], v[48:49], v[36:37]
	v_cvt_pk_bf16_f32 v56, v56, v57
	v_cvt_pk_bf16_f32 v57, v58, v59
	v_pk_fma_f32 v[50:51], v[50:51], v[76:77], v[40:41]
	s_nop 1
	v_add_f32_dpp v108, v108, v108 quad_perm:[2,3,0,1] row_mask:0xf bank_mask:0xf
	v_add_f32_dpp v109, v109, v109 quad_perm:[2,3,0,1] row_mask:0xf bank_mask:0xf
	global_store_dwordx2 v[104:105], v[56:57], off
	v_cvt_pk_bf16_f32 v48, v48, v49
	v_pk_fma_f32 v[84:85], v[98:99], v[84:85], v[38:39]
	v_pk_fma_f32 v[54:55], v[54:55], v[78:79], v[42:43]
	s_nop 1
	v_add_f32_dpp v108, v108, v108 row_half_mirror row_mask:0xf bank_mask:0xf
	v_add_f32_dpp v109, v109, v109 row_half_mirror row_mask:0xf bank_mask:0xf
	v_cvt_pk_bf16_f32 v49, v84, v85
	global_store_dwordx2 v[104:105], v[48:49], off offset:512
	v_cvt_pk_bf16_f32 v48, v50, v51
	v_cvt_pk_bf16_f32 v49, v54, v55
	s_nop 1
	v_add_f32_dpp v108, v108, v108 row_mirror row_mask:0xf bank_mask:0xf
	v_add_f32_dpp v109, v109, v109 row_mirror row_mask:0xf bank_mask:0xf
	global_store_dwordx2 v[104:105], v[48:49], off offset:1024
	v_lshl_add_u64 v[106:107], v[88:89], 0, s[8:9]
	v_pk_fma_f32 v[74:75], v[94:95], v[74:75], v[34:35]
	v_pk_fma_f32 v[72:73], v[96:97], v[72:73], v[32:33]
	v_mov_b32_e32 v110, v108
	v_mov_b32_e32 v111, v109
	s_nop 1
	v_permlane16_swap_b32_e32 v108, v110
	v_permlane16_swap_b32_e32 v109, v111
	v_pk_add_f32 v[108:109], v[108:109], v[110:111]
	s_lshl_b64 s[4:5], s[10:11], 11
	v_pk_fma_f32 v[102:103], v[98:99], v[102:103], v[38:39]
	v_pk_fma_f32 v[64:65], v[100:101], v[64:65], v[36:37]
	v_lshl_add_u64 v[70:71], v[88:89], 0, s[4:5]
	v_mov_b32_e32 v110, v108
	v_mov_b32_e32 v111, v109
	s_nop 1
	v_permlane32_swap_b32_e32 v108, v110
	v_permlane32_swap_b32_e32 v109, v111
	v_pk_add_f32 v[110:111], v[108:109], v[110:111]
	v_lshl_add_u64 v[108:109], v[88:89], 0, s[0:1]
	v_pk_fma_f32 v[92:93], v[110:111], s[20:21], v[92:93] op_sel_hi:[1,0,0]
	v_pk_fma_f32 v[68:69], v[78:79], v[68:69], v[42:43]
	v_mul_f32_e32 v58, 0x4b800000, v93
	v_cmp_gt_f32_e64 s[0:1], s18, v93
	v_mul_f32_e32 v59, 0x4b800000, v92
	v_cmp_gt_f32_e32 vcc, s18, v92
	v_cndmask_b32_e64 v56, v93, v58, s[0:1]
	v_rsq_f32_e32 v50, v56
	v_cndmask_b32_e32 v57, v92, v59, vcc
	v_rsq_f32_e32 v51, v57
	v_pk_fma_f32 v[66:67], v[76:77], v[66:67], v[40:41]
	s_add_i32 s2, s2, s24
	s_cmpk_lt_i32 s14, 0x2400
	s_waitcnt vmcnt(3)
	v_pk_fma_f32 v[52:53], v[52:53], v[80:81], v[44:45]
	v_pk_fma_f32 v[86:87], v[86:87], v[82:83], v[46:47]
	v_cvt_pk_bf16_f32 v48, v52, v53
	v_mul_f32_e32 v52, 0x45800000, v50
	v_cvt_pk_bf16_f32 v49, v86, v87
	global_store_dwordx2 v[104:105], v[48:49], off offset:1536
	v_cvt_pk_bf16_f32 v48, v72, v73
	v_cvt_pk_bf16_f32 v49, v74, v75
	v_cndmask_b32_e64 v50, v50, v52, s[0:1]
	global_store_dwordx2 v[106:107], v[48:49], off
	v_cvt_pk_bf16_f32 v48, v64, v65
	v_cvt_pk_bf16_f32 v49, v102, v103
	v_mul_f32_e32 v53, 0x45800000, v51
	v_pk_mul_f32 v[12:13], v[12:13], v[50:51] op_sel_hi:[1,0]
	v_pk_mul_f32 v[8:9], v[8:9], v[50:51] op_sel_hi:[1,0]
	v_pk_mul_f32 v[4:5], v[4:5], v[50:51] op_sel_hi:[1,0]
	v_pk_mul_f32 v[0:1], v[0:1], v[50:51] op_sel_hi:[1,0]
	global_store_dwordx2 v[106:107], v[48:49], off offset:512
	v_cvt_pk_bf16_f32 v48, v66, v67
	v_cvt_pk_bf16_f32 v49, v68, v69
	v_cndmask_b32_e32 v52, v51, v53, vcc
	v_pk_mul_f32 v[14:15], v[14:15], v[50:51] op_sel_hi:[1,0]
	v_pk_mul_f32 v[10:11], v[10:11], v[50:51] op_sel_hi:[1,0]
	v_pk_mul_f32 v[6:7], v[6:7], v[50:51] op_sel_hi:[1,0]
	v_pk_mul_f32 v[2:3], v[2:3], v[50:51] op_sel_hi:[1,0]
	v_pk_fma_f32 v[12:13], v[96:97], v[12:13], v[32:33]
	v_pk_fma_f32 v[8:9], v[100:101], v[8:9], v[36:37]
	v_pk_fma_f32 v[4:5], v[76:77], v[4:5], v[40:41]
	v_pk_fma_f32 v[0:1], v[0:1], v[80:81], v[44:45]
	v_pk_fma_f32 v[62:63], v[62:63], v[82:83], v[46:47]
	v_pk_fma_f32 v[60:61], v[60:61], v[80:81], v[44:45]
	global_store_dwordx2 v[106:107], v[48:49], off offset:1024
	v_cvt_pk_bf16_f32 v48, v60, v61
	v_cvt_pk_bf16_f32 v49, v62, v63
	global_store_dwordx2 v[106:107], v[48:49], off offset:1536
	v_pk_mul_f32 v[28:29], v[28:29], v[52:53] op_sel_hi:[1,0]
	v_pk_mul_f32 v[30:31], v[30:31], v[52:53] op_sel_hi:[1,0]
	v_pk_fma_f32 v[14:15], v[94:95], v[14:15], v[34:35]
	v_pk_fma_f32 v[10:11], v[98:99], v[10:11], v[38:39]
	v_pk_fma_f32 v[6:7], v[78:79], v[6:7], v[42:43]
	v_pk_fma_f32 v[2:3], v[2:3], v[82:83], v[46:47]
	v_cvt_pk_bf16_f32 v12, v12, v13
	v_cvt_pk_bf16_f32 v13, v14, v15
	global_store_dwordx2 v[70:71], v[12:13], off
	v_cvt_pk_bf16_f32 v8, v8, v9
	v_cvt_pk_bf16_f32 v9, v10, v11
	global_store_dwordx2 v[70:71], v[8:9], off offset:512
	v_cvt_pk_bf16_f32 v4, v4, v5
	v_cvt_pk_bf16_f32 v5, v6, v7
	global_store_dwordx2 v[70:71], v[4:5], off offset:1024
	v_cvt_pk_bf16_f32 v0, v0, v1
	v_cvt_pk_bf16_f32 v1, v2, v3
	v_pk_mul_f32 v[24:25], v[24:25], v[52:53] op_sel_hi:[1,0]
	v_pk_mul_f32 v[26:27], v[26:27], v[52:53] op_sel_hi:[1,0]
	v_pk_fma_f32 v[30:31], v[94:95], v[30:31], v[34:35]
	v_pk_fma_f32 v[28:29], v[96:97], v[28:29], v[32:33]
	global_store_dwordx2 v[70:71], v[0:1], off offset:1536
	v_cvt_pk_bf16_f32 v0, v28, v29
	v_cvt_pk_bf16_f32 v1, v30, v31
	v_pk_mul_f32 v[20:21], v[20:21], v[52:53] op_sel_hi:[1,0]
	v_pk_mul_f32 v[22:23], v[22:23], v[52:53] op_sel_hi:[1,0]
	v_pk_fma_f32 v[26:27], v[98:99], v[26:27], v[38:39]
	v_pk_fma_f32 v[24:25], v[100:101], v[24:25], v[36:37]
	global_store_dwordx2 v[108:109], v[0:1], off
	v_cvt_pk_bf16_f32 v0, v24, v25
	v_cvt_pk_bf16_f32 v1, v26, v27
	v_pk_mul_f32 v[16:17], v[16:17], v[52:53] op_sel_hi:[1,0]
	v_pk_mul_f32 v[18:19], v[18:19], v[52:53] op_sel_hi:[1,0]
	v_pk_fma_f32 v[22:23], v[78:79], v[22:23], v[42:43]
	v_pk_fma_f32 v[20:21], v[76:77], v[20:21], v[40:41]
	global_store_dwordx2 v[108:109], v[0:1], off offset:512
	v_cvt_pk_bf16_f32 v0, v20, v21
	v_cvt_pk_bf16_f32 v1, v22, v23
	v_pk_fma_f32 v[18:19], v[18:19], v[82:83], v[46:47]
	v_pk_fma_f32 v[16:17], v[16:17], v[80:81], v[44:45]
	global_store_dwordx2 v[108:109], v[0:1], off offset:1024
	v_cvt_pk_bf16_f32 v0, v16, v17
	v_cvt_pk_bf16_f32 v1, v18, v19
	global_store_dwordx2 v[108:109], v[0:1], off offset:1536
	s_cbranch_scc1 .LBB0_492
